# E33: E32 + hoisted bias LDS reads + wait-state minimisation (hazard nop before each srcC=0 MFMA removed), later code kept at its 64-byte phase
# speedup vs baseline: 1.0042x; 1.0042x over previous
; template <class MB> __device__ __forceinline__ void la_soft(LA& st, f32x16& s, const TP& t, bf16x8& pf0, bf16x8& pf1) {
;     float mx = NEGBIG;
; #pragma unroll
;     for (int r = 0; r < 16; ++r) { s[r] = MB::apply(t, r, s[r]); mx = __builtin_fmaxf(mx, s[r]); }
;     { auto rr = __builtin_amdgcn_permlane32_swap(__float_as_uint(mx), __float_as_uint(mx), false, false); mx = __builtin_fmaxf(__uint_as_float(rr[0]), __uint_as_float(rr[1])); }
;     if (__any(mx > st.m)) { const float mn = __builtin_fmaxf(st.m, mx), alpha = __builtin_amdgcn_exp2f(st.m - mn); st.m = mn; st.l *= alpha; st.o0 *= alpha; st.o1 *= alpha; }
; template <class MB, int V1, class VS> __device__ __forceinline__ void la_step2(LA& sa, LA& sb, const bf16x8 (&qa)[4], const bf16x8 (&qb)[4], Frag& f, const char* kb, const VS& vs, const TP& t, const TP& n) {
;     bf16x8 pa0, pa1;
;     { f32x16 s0 = zero16();
; #pragma unroll
;       for (int d0 = 0; d0 < 4; ++d0) s0 = __builtin_amdgcn_mfma_f32_32x32x16_bf16(f.k[d0], qa[d0], s0, 0, 0, 0);
;       la_soft<MB>(sa, s0, t, pa0, pa1); }
.LBB0_661:
	s_add_i32 s4, s7, s9
	s_addk_i32 s4, 0xffa0
	s_cmpk_lt_u32 s4, 0x4000
	v_lshl_add_u32 v64, v64, 1, v148
	s_cselect_b64 s[4:5], -1, 0
	s_cmpk_lg_i32 s9, 0xc0
	v_add_u32_e32 v65, 0x9000, v64
	s_cselect_b64 s[10:11], -1, 0
	ds_read_b128 v[136:139], v65 offset:41472
	ds_read_b128 v[128:131], v65 offset:41504
	ds_read_b128 v[140:143], v64 offset:36864
	ds_read_b128 v[132:135], v64 offset:36896
	s_and_b64 vcc, s[10:11], s[4:5]
	v_add_u32_e32 v150, 0x80, v152
	v_mov_b32_e32 v64, s53
	v_cndmask_b32_e32 v167, v64, v150, vcc
	ds_read2_b32 v[154:155], v167 offset1:1
	ds_read2_b32 v[234:235], v167 offset0:2 offset1:3
	ds_read2_b32 v[236:237], v167 offset0:4 offset1:5
	ds_read2_b32 v[238:239], v167 offset0:6 offset1:7
	ds_read2_b32 v[240:241], v167 offset0:16 offset1:17
	ds_read2_b32 v[242:243], v167 offset0:18 offset1:19
	ds_read2_b32 v[244:245], v167 offset0:20 offset1:21
	ds_read2_b32 v[246:247], v167 offset0:22 offset1:23
	s_waitcnt vmcnt(3)
	v_mfma_f32_32x32x16_bf16 v[64:79], v[124:127], v[96:99], 0
	s_waitcnt vmcnt(2)
	v_mfma_f32_32x32x16_bf16 v[64:79], v[120:123], v[88:91], v[64:79]
	s_waitcnt vmcnt(1)
	v_mfma_f32_32x32x16_bf16 v[64:79], v[116:119], v[92:95], v[64:79]
	s_waitcnt vmcnt(0)
	v_mfma_f32_32x32x16_bf16 v[64:79], v[112:115], v[100:103], v[64:79]
	s_waitcnt lgkmcnt(0)
	s_nop 10
	v_add_f32_e32 v154, v64, v154
	v_add_f32_e32 v153, v65, v155
	v_max3_f32 v157, v154, s2, v153
	v_add_f32_e32 v156, v66, v234
	v_add_f32_e32 v155, v67, v235
	v_max3_f32 v66, v157, v156, v155
	v_add_f32_e32 v158, v68, v236
	v_add_f32_e32 v157, v69, v237
	v_max3_f32 v66, v66, v158, v157
	v_add_f32_e32 v160, v70, v238
	v_add_f32_e32 v159, v71, v239
	v_max3_f32 v66, v66, v160, v159
	v_add_f32_e32 v162, v72, v240
	v_add_f32_e32 v161, v73, v241
	v_max3_f32 v66, v66, v162, v161
	v_add_f32_e32 v166, v74, v242
	v_add_f32_e32 v165, v75, v243
	v_max3_f32 v66, v66, v166, v165
	v_add_f32_e32 v164, v76, v244
	v_add_f32_e32 v163, v77, v245
	v_max3_f32 v66, v66, v164, v163
	v_add_f32_e32 v168, v78, v246
	v_add_f32_e32 v167, v79, v247
	v_max3_f32 v64, v66, v168, v167
	v_mov_b32_e32 v65, v64
	s_nop 1
	v_permlane32_swap_b32_e32 v64, v65
	v_max_f32_e32 v65, v65, v65
	v_max_f32_e32 v64, v64, v64
	v_max_f32_e32 v64, v64, v65
	v_cmp_gt_f32_e32 vcc, v64, v151
	s_cbranch_vccz .LBB0_663
	v_max_f32_e32 v64, v64, v64
	v_max_f32_e32 v65, v151, v151
	v_max_f32_e32 v65, v65, v64
	v_sub_f32_e32 v64, v151, v65
	v_exp_f32_e32 v64, v64
	v_mov_b32_e32 v151, v65
	v_mul_f32_e32 v147, v64, v147
	v_pk_mul_f32 v[46:47], v[64:65], v[46:47] op_sel_hi:[0,1]
	v_pk_mul_f32 v[44:45], v[64:65], v[44:45] op_sel_hi:[0,1]
	v_pk_mul_f32 v[42:43], v[64:65], v[42:43] op_sel_hi:[0,1]
	v_pk_mul_f32 v[40:41], v[64:65], v[40:41] op_sel_hi:[0,1]
	v_pk_mul_f32 v[38:39], v[64:65], v[38:39] op_sel_hi:[0,1]
	v_pk_mul_f32 v[36:37], v[64:65], v[36:37] op_sel_hi:[0,1]
	v_pk_mul_f32 v[34:35], v[64:65], v[34:35] op_sel_hi:[0,1]
	v_pk_mul_f32 v[32:33], v[64:65], v[32:33] op_sel_hi:[0,1]
	v_pk_mul_f32 v[62:63], v[64:65], v[62:63] op_sel_hi:[0,1]
	v_pk_mul_f32 v[60:61], v[64:65], v[60:61] op_sel_hi:[0,1]
	v_pk_mul_f32 v[58:59], v[64:65], v[58:59] op_sel_hi:[0,1]
	v_pk_mul_f32 v[56:57], v[64:65], v[56:57] op_sel_hi:[0,1]
	v_pk_mul_f32 v[54:55], v[64:65], v[54:55] op_sel_hi:[0,1]
	v_pk_mul_f32 v[52:53], v[64:65], v[52:53] op_sel_hi:[0,1]
	v_pk_mul_f32 v[50:51], v[64:65], v[50:51] op_sel_hi:[0,1]
	v_pk_mul_f32 v[48:49], v[64:65], v[48:49] op_sel_hi:[0,1]
; __device__ __forceinline__ unsigned cvt_pk_bf16(float lo, float hi) { f32x2_c v = {lo, hi}; bf16x2_c b = __builtin_convertvector(v, bf16x2_c); return __builtin_bit_cast(unsigned, b); }
; template <class MB> __device__ __forceinline__ void la_soft(LA& st, f32x16& s, const TP& t, bf16x8& pf0, bf16x8& pf1) {
;     ...
;     float rs = 0.f;
; #pragma unroll
;     for (int r = 0; r < 16; ++r) { s[r] = __builtin_amdgcn_exp2f(s[r] - st.m); rs += s[r]; }
;     st.l += rs;
;     u32x4 p0, p1;
; #pragma unroll
;     for (int e = 0; e < 4; ++e) { p0[e] = cvt_pk_bf16(s[2 * e], s[2 * e + 1]); p1[e] = cvt_pk_bf16(s[8 + 2 * e], s[8 + 2 * e + 1]); }
;     pf0 = __builtin_bit_cast(bf16x8, p0); pf1 = __builtin_bit_cast(bf16x8, p1);
; }
; template <class MB, int V1, class VS> __device__ __forceinline__ void la_step2(LA& sa, LA& sb, const bf16x8 (&qa)[4], const bf16x8 (&qb)[4], Frag& f, const char* kb, const VS& vs, const TP& t, const TP& n) {
;     bf16x8 pa0, pa1;
;     { f32x16 s0 = zero16();
; #pragma unroll
;       for (int d0 = 0; d0 < 4; ++d0) s0 = __builtin_amdgcn_mfma_f32_32x32x16_bf16(f.k[d0], qa[d0], s0, 0, 0, 0);
;       la_soft<MB>(sa, s0, t, pa0, pa1); }
;     f32x16 s1 = zero16();
; #pragma unroll
;     for (int d0 = 0; d0 < 4; ++d0) s1 = __builtin_amdgcn_mfma_f32_32x32x16_bf16(f.k[d0], qb[d0], s1, 0, 0, 0);
;     la_loadK(f, kb, n);
;     sa.o0 = __builtin_amdgcn_mfma_f32_32x32x16_bf16(f.v[0], pa0, sa.o0, 0, 0, 0); sa.o1 = __builtin_amdgcn_mfma_f32_32x32x16_bf16(f.v[2], pa0, sa.o1, 0, 0, 0);
;     sa.o0 = __builtin_amdgcn_mfma_f32_32x32x16_bf16(f.v[1], pa1, sa.o0, 0, 0, 0); sa.o1 = __builtin_amdgcn_mfma_f32_32x32x16_bf16(f.v[3], pa1, sa.o1, 0, 0, 0);
;     { bf16x8 pb0, pb1; const TP tb = MB::second(t);
;       la_soft<MB>(sb, s1, tb, pb0, pb1);
;       sb.o0 = __builtin_amdgcn_mfma_f32_32x32x16_bf16(f.v[0], pb0, sb.o0, 0, 0, 0); sb.o1 = __builtin_amdgcn_mfma_f32_32x32x16_bf16(f.v[2], pb0, sb.o1, 0, 0, 0);
;       sb.o0 = __builtin_amdgcn_mfma_f32_32x32x16_bf16(f.v[1], pb1, sb.o0, 0, 0, 0); sb.o1 = __builtin_amdgcn_mfma_f32_32x32x16_bf16(f.v[3], pb1, sb.o1, 0, 0, 0); }
.LBB0_663:
	s_cmp_lg_u32 s9, 32
	s_cselect_b64 s[10:11], -1, 0
	s_and_b64 vcc, s[10:11], s[4:5]
	s_cmpk_lg_i32 s9, 0xc0
	s_cselect_b32 s4, s9, 0xa0
	s_add_i32 s5, s8, s4
	s_cmpk_lt_u32 s5, 0x4000
	s_cselect_b32 s5, s5, s7
	v_or_b32_e32 v64, s5, v185
	v_mul_lo_u32 v64, v64, s67
	v_add_lshl_u32 v175, v64, v181, 1
	v_mov_b32_e32 v174, s53
	v_cndmask_b32_e32 v180, v174, v152, vcc
	v_mfma_f32_32x32x16_bf16 v[64:79], v[124:127], v[80:83], 0
	v_sub_f32_e32 v124, v154, v151
	v_exp_f32_e32 v154, v124
	v_sub_f32_e32 v124, v153, v151
	v_exp_f32_e32 v153, v124
	v_sub_f32_e32 v124, v156, v151
	v_exp_f32_e32 v156, v124
	v_sub_f32_e32 v124, v155, v151
	v_mfma_f32_32x32x16_bf16 v[64:79], v[120:123], v[84:87], v[64:79]
	v_sub_f32_e32 v120, v158, v151
	v_exp_f32_e32 v158, v120
	v_sub_f32_e32 v120, v157, v151
	v_exp_f32_e32 v157, v120
	v_sub_f32_e32 v120, v160, v151
	v_exp_f32_e32 v155, v124
	v_exp_f32_e32 v160, v120
	v_mfma_f32_32x32x16_bf16 v[64:79], v[116:119], v[104:107], v[64:79]
	v_sub_f32_e32 v116, v159, v151
	v_exp_f32_e32 v159, v116
	v_sub_f32_e32 v116, v162, v151
	v_exp_f32_e32 v162, v116
	v_sub_f32_e32 v116, v161, v151
	v_exp_f32_e32 v161, v116
	v_sub_f32_e32 v116, v166, v151
	v_exp_f32_e32 v166, v116
	v_sub_f32_e32 v116, v164, v151
	v_exp_f32_e32 v164, v116
	v_sub_f32_e32 v116, v163, v151
	v_mfma_f32_32x32x16_bf16 v[64:79], v[112:115], v[108:111], v[64:79]
	v_sub_f32_e32 v112, v165, v151
	v_exp_f32_e32 v169, v116
	v_sub_f32_e32 v116, v168, v151
	v_exp_f32_e32 v165, v112
	v_cvt_pk_bf16_f32 v112, v154, v153
	v_cvt_pk_bf16_f32 v113, v156, v155
	v_cvt_pk_bf16_f32 v114, v158, v157
	v_cvt_pk_bf16_f32 v115, v160, v159
	v_exp_f32_e32 v168, v116
	v_sub_f32_e32 v116, v167, v151
	v_mfma_f32_32x32x16_bf16 v[32:47], v[140:143], v[112:115], v[32:47]
	v_exp_f32_e32 v163, v116
	global_load_dwordx4 v[124:127], v175, s[74:75]
	global_load_dwordx4 v[120:123], v175, s[74:75] offset:32
	v_cvt_pk_bf16_f32 v170, v162, v161
	v_cvt_pk_bf16_f32 v171, v166, v165
	v_cvt_pk_bf16_f32 v172, v164, v169
	v_cvt_pk_bf16_f32 v173, v168, v163
	v_mfma_f32_32x32x16_bf16 v[48:63], v[136:139], v[112:115], v[48:63]
	global_load_dwordx4 v[116:119], v175, s[74:75] offset:64
	global_load_dwordx4 v[112:115], v175, s[74:75] offset:96
	ds_read2_b32 v[174:175], v180 offset1:1
	ds_read2_b32 v[176:177], v180 offset0:2 offset1:3
	ds_read2_b32 v[178:179], v180 offset0:4 offset1:5
	ds_read2_b32 v[182:183], v180 offset0:6 offset1:7
	s_waitcnt lgkmcnt(3)
	v_add_f32_e32 v174, v64, v174
	v_mfma_f32_32x32x16_bf16 v[32:47], v[132:135], v[170:173], v[32:47]
	s_waitcnt lgkmcnt(1)
	v_add_f32_e32 v167, v68, v178
	v_add_f32_e32 v152, v69, v179
	s_waitcnt lgkmcnt(0)
	v_add_f32_e32 v70, v70, v182
	v_add_f32_e32 v69, v71, v183
	v_mfma_f32_32x32x16_bf16 v[48:63], v[128:131], v[170:173], v[48:63]
	v_add_f32_e32 v173, v65, v175
	v_max3_f32 v64, v174, s2, v173
	v_add_f32_e32 v171, v66, v176
	v_add_f32_e32 v170, v67, v177
	v_max3_f32 v64, v64, v171, v170
	v_max3_f32 v66, v64, v167, v152
	ds_read2_b32 v[64:65], v180 offset0:16 offset1:17
	v_max3_f32 v68, v66, v70, v69
	ds_read2_b32 v[66:67], v180 offset0:18 offset1:19
	ds_read2_b32 v[176:177], v180 offset0:20 offset1:21
	ds_read2_b32 v[178:179], v180 offset0:22 offset1:23
	s_waitcnt lgkmcnt(3)
	v_add_f32_e32 v172, v72, v64
	v_add_f32_e32 v72, v73, v65
	v_max3_f32 v64, v68, v172, v72
	s_waitcnt lgkmcnt(2)
	v_add_f32_e32 v71, v74, v66
	v_add_f32_e32 v67, v75, v67
	v_max3_f32 v64, v64, v71, v67
	s_waitcnt lgkmcnt(1)
	v_add_f32_e32 v68, v76, v176
	v_add_f32_e32 v65, v77, v177
	v_max3_f32 v73, v64, v68, v65
	s_waitcnt lgkmcnt(0)
	v_add_f32_e32 v66, v78, v178
	v_add_f32_e32 v64, v79, v179
	v_max3_f32 v73, v73, v66, v64
	v_mov_b32_e32 v74, v73
	s_nop 1
	v_permlane32_swap_b32_e32 v73, v74
	v_max_f32_e32 v74, v74, v74
	v_max_f32_e32 v73, v73, v73
	v_max_f32_e32 v73, v73, v74
	v_cmp_gt_f32_e32 vcc, v73, v145
	s_cbranch_vccz .LBB0_665
	v_max_f32_e32 v73, v73, v73
	v_max_f32_e32 v74, v145, v145
	v_max_f32_e32 v73, v74, v73
	v_sub_f32_e32 v74, v145, v73
	v_exp_f32_e32 v74, v74
	v_mov_b32_e32 v145, v73
	v_mul_f32_e32 v144, v74, v144
	v_pk_mul_f32 v[14:15], v[74:75], v[14:15] op_sel_hi:[0,1]
	v_pk_mul_f32 v[12:13], v[74:75], v[12:13] op_sel_hi:[0,1]
	v_pk_mul_f32 v[10:11], v[74:75], v[10:11] op_sel_hi:[0,1]
	v_pk_mul_f32 v[8:9], v[74:75], v[8:9] op_sel_hi:[0,1]
	v_pk_mul_f32 v[6:7], v[74:75], v[6:7] op_sel_hi:[0,1]
	v_pk_mul_f32 v[4:5], v[74:75], v[4:5] op_sel_hi:[0,1]
	v_pk_mul_f32 v[2:3], v[74:75], v[2:3] op_sel_hi:[0,1]
	v_pk_mul_f32 v[0:1], v[74:75], v[0:1] op_sel_hi:[0,1]
	v_pk_mul_f32 v[30:31], v[74:75], v[30:31] op_sel_hi:[0,1]
	v_pk_mul_f32 v[28:29], v[74:75], v[28:29] op_sel_hi:[0,1]
	v_pk_mul_f32 v[26:27], v[74:75], v[26:27] op_sel_hi:[0,1]
	v_pk_mul_f32 v[24:25], v[74:75], v[24:25] op_sel_hi:[0,1]
	v_pk_mul_f32 v[22:23], v[74:75], v[22:23] op_sel_hi:[0,1]
	v_pk_mul_f32 v[20:21], v[74:75], v[20:21] op_sel_hi:[0,1]
	v_pk_mul_f32 v[18:19], v[74:75], v[18:19] op_sel_hi:[0,1]
	v_pk_mul_f32 v[16:17], v[74:75], v[16:17] op_sel_hi:[0,1]

; template <class MB> __device__ __forceinline__ void la_soft(LA& st, f32x16& s, const TP& t, bf16x8& pf0, bf16x8& pf1) {
;     float mx = NEGBIG;
; #pragma unroll
;     for (int r = 0; r < 16; ++r) { s[r] = MB::apply(t, r, s[r]); mx = __builtin_fmaxf(mx, s[r]); }
;     { auto rr = __builtin_amdgcn_permlane32_swap(__float_as_uint(mx), __float_as_uint(mx), false, false); mx = __builtin_fmaxf(__uint_as_float(rr[0]), __uint_as_float(rr[1])); }
;     if (__any(mx > st.m)) { const float mn = __builtin_fmaxf(st.m, mx), alpha = __builtin_amdgcn_exp2f(st.m - mn); st.m = mn; st.l *= alpha; st.o0 *= alpha; st.o1 *= alpha; }
; template <class MB, int V1, class VS> __device__ __forceinline__ void la_step2(LA& sa, LA& sb, const bf16x8 (&qa)[4], const bf16x8 (&qb)[4], Frag& f, const char* kb, const VS& vs, const TP& t, const TP& n) {
;     bf16x8 pa0, pa1;
;     { f32x16 s0 = zero16();
; #pragma unroll
;       for (int d0 = 0; d0 < 4; ++d0) s0 = __builtin_amdgcn_mfma_f32_32x32x16_bf16(f.k[d0], qa[d0], s0, 0, 0, 0);
;       la_soft<MB>(sa, s0, t, pa0, pa1); }
.LBB0_673:
	v_lshlrev_b32_e32 v64, 1, v73
	v_ashrrev_i32_e32 v65, 31, v64
	v_lshl_add_u64 v[64:65], s[6:7], 0, v[64:65]
	v_add_co_u32_e32 v66, vcc, s80, v64
	s_add_i32 s8, s11, s13
	s_nop 0
	v_addc_co_u32_e32 v67, vcc, 0, v65, vcc
	global_load_dwordx4 v[128:131], v[66:67], off offset:2080
	global_load_dwordx4 v[136:139], v[66:67], off offset:2048
	global_load_dwordx4 v[132:135], v[64:65], off offset:32
	global_load_dwordx4 v[140:143], v[64:65], off
	s_cmpk_lt_u32 s8, 0x4000
	s_cselect_b64 s[8:9], -1, 0
	s_cmpk_lg_i32 s12, 0x480
	s_cselect_b64 s[14:15], -1, 0
	v_add_u32_e32 v197, s12, v195
	s_and_b64 vcc, s[14:15], s[8:9]
	v_add_u32_e32 v64, 0x80, v197
	v_mov_b32_e32 v65, s53
	v_cndmask_b32_e32 v212, v65, v64, vcc
	ds_read2_b32 v[200:201], v212 offset1:1
	ds_read2_b32 v[234:235], v212 offset0:2 offset1:3
	ds_read2_b32 v[236:237], v212 offset0:4 offset1:5
	ds_read2_b32 v[238:239], v212 offset0:6 offset1:7
	ds_read2_b32 v[240:241], v212 offset0:16 offset1:17
	ds_read2_b32 v[242:243], v212 offset0:18 offset1:19
	ds_read2_b32 v[244:245], v212 offset0:20 offset1:21
	ds_read2_b32 v[246:247], v212 offset0:22 offset1:23
	s_waitcnt vmcnt(7)
	v_mfma_f32_32x32x16_bf16 v[64:79], v[124:127], v[80:83], 0
	s_waitcnt vmcnt(6)
	v_mfma_f32_32x32x16_bf16 v[64:79], v[120:123], v[84:87], v[64:79]
	s_waitcnt vmcnt(5)
	v_mfma_f32_32x32x16_bf16 v[64:79], v[116:119], v[96:99], v[64:79]
	s_waitcnt vmcnt(4)
	v_mfma_f32_32x32x16_bf16 v[64:79], v[112:115], v[100:103], v[64:79]
	s_waitcnt lgkmcnt(0)
	s_nop 10
	v_add_f32_e32 v199, v64, v200
	v_add_f32_e32 v198, v65, v201
	v_max3_f32 v202, v199, s2, v198
	v_add_f32_e32 v201, v66, v234
	v_add_f32_e32 v200, v67, v235
	v_max3_f32 v66, v202, v201, v200
	v_add_f32_e32 v203, v68, v236
	v_add_f32_e32 v202, v69, v237
	v_max3_f32 v66, v66, v203, v202
	v_add_f32_e32 v205, v70, v238
	v_add_f32_e32 v204, v71, v239
	v_max3_f32 v66, v66, v205, v204
	v_add_f32_e32 v207, v72, v240
	v_add_f32_e32 v206, v73, v241
	v_max3_f32 v66, v66, v207, v206
	v_add_f32_e32 v211, v74, v242
	v_add_f32_e32 v210, v75, v243
	v_max3_f32 v66, v66, v211, v210
	v_add_f32_e32 v209, v76, v244
	v_add_f32_e32 v208, v77, v245
	v_max3_f32 v66, v66, v209, v208
	v_add_f32_e32 v213, v78, v246
	v_add_f32_e32 v212, v79, v247
	v_max3_f32 v64, v66, v213, v212
	v_mov_b32_e32 v65, v64
	s_nop 1
	v_permlane32_swap_b32_e32 v64, v65
	v_max_f32_e32 v65, v65, v65
	v_max_f32_e32 v64, v64, v64
	v_max_f32_e32 v64, v64, v65
	v_cmp_gt_f32_e32 vcc, v64, v196
	s_cbranch_vccz .LBB0_675
	v_max_f32_e32 v64, v64, v64
	v_max_f32_e32 v65, v196, v196
	v_max_f32_e32 v65, v65, v64
	v_sub_f32_e32 v64, v196, v65
	v_exp_f32_e32 v64, v64
	v_mov_b32_e32 v196, v65
	v_mul_f32_e32 v193, v193, v64
	v_pk_mul_f32 v[62:63], v[62:63], v[64:65] op_sel_hi:[1,0]
	v_pk_mul_f32 v[60:61], v[60:61], v[64:65] op_sel_hi:[1,0]
	v_pk_mul_f32 v[58:59], v[58:59], v[64:65] op_sel_hi:[1,0]
	v_pk_mul_f32 v[56:57], v[56:57], v[64:65] op_sel_hi:[1,0]
	v_pk_mul_f32 v[54:55], v[54:55], v[64:65] op_sel_hi:[1,0]
	v_pk_mul_f32 v[52:53], v[52:53], v[64:65] op_sel_hi:[1,0]
	v_pk_mul_f32 v[50:51], v[50:51], v[64:65] op_sel_hi:[1,0]
	v_pk_mul_f32 v[48:49], v[48:49], v[64:65] op_sel_hi:[1,0]
	v_pk_mul_f32 v[46:47], v[46:47], v[64:65] op_sel_hi:[1,0]
	v_pk_mul_f32 v[44:45], v[44:45], v[64:65] op_sel_hi:[1,0]
	v_pk_mul_f32 v[42:43], v[42:43], v[64:65] op_sel_hi:[1,0]
	v_pk_mul_f32 v[40:41], v[40:41], v[64:65] op_sel_hi:[1,0]
	v_pk_mul_f32 v[38:39], v[38:39], v[64:65] op_sel_hi:[1,0]
	v_pk_mul_f32 v[36:37], v[36:37], v[64:65] op_sel_hi:[1,0]
	v_pk_mul_f32 v[34:35], v[34:35], v[64:65] op_sel_hi:[1,0]
	v_pk_mul_f32 v[32:33], v[32:33], v[64:65] op_sel_hi:[1,0]
; __device__ __forceinline__ unsigned cvt_pk_bf16(float lo, float hi) { f32x2_c v = {lo, hi}; bf16x2_c b = __builtin_convertvector(v, bf16x2_c); return __builtin_bit_cast(unsigned, b); }
; template <class MB> __device__ __forceinline__ void la_soft(LA& st, f32x16& s, const TP& t, bf16x8& pf0, bf16x8& pf1) {
;     ...
;     float rs = 0.f;
; #pragma unroll
;     for (int r = 0; r < 16; ++r) { s[r] = __builtin_amdgcn_exp2f(s[r] - st.m); rs += s[r]; }
;     st.l += rs;
;     u32x4 p0, p1;
; #pragma unroll
;     for (int e = 0; e < 4; ++e) { p0[e] = cvt_pk_bf16(s[2 * e], s[2 * e + 1]); p1[e] = cvt_pk_bf16(s[8 + 2 * e], s[8 + 2 * e + 1]); }
;     pf0 = __builtin_bit_cast(bf16x8, p0); pf1 = __builtin_bit_cast(bf16x8, p1);
; }
; template <class MB, int V1, class VS> __device__ __forceinline__ void la_step2(LA& sa, LA& sb, const bf16x8 (&qa)[4], const bf16x8 (&qb)[4], Frag& f, const char* kb, const VS& vs, const TP& t, const TP& n) {
;     bf16x8 pa0, pa1;
;     { f32x16 s0 = zero16();
; #pragma unroll
;       for (int d0 = 0; d0 < 4; ++d0) s0 = __builtin_amdgcn_mfma_f32_32x32x16_bf16(f.k[d0], qa[d0], s0, 0, 0, 0);
;       la_soft<MB>(sa, s0, t, pa0, pa1); }
;     f32x16 s1 = zero16();
; #pragma unroll
;     for (int d0 = 0; d0 < 4; ++d0) s1 = __builtin_amdgcn_mfma_f32_32x32x16_bf16(f.k[d0], qb[d0], s1, 0, 0, 0);
;     la_loadK(f, kb, n);
;     sa.o0 = __builtin_amdgcn_mfma_f32_32x32x16_bf16(f.v[0], pa0, sa.o0, 0, 0, 0); sa.o1 = __builtin_amdgcn_mfma_f32_32x32x16_bf16(f.v[2], pa0, sa.o1, 0, 0, 0);
;     sa.o0 = __builtin_amdgcn_mfma_f32_32x32x16_bf16(f.v[1], pa1, sa.o0, 0, 0, 0); sa.o1 = __builtin_amdgcn_mfma_f32_32x32x16_bf16(f.v[3], pa1, sa.o1, 0, 0, 0);
;     { bf16x8 pb0, pb1; const TP tb = MB::second(t);
;       la_soft<MB>(sb, s1, tb, pb0, pb1);
;       sb.o0 = __builtin_amdgcn_mfma_f32_32x32x16_bf16(f.v[0], pb0, sb.o0, 0, 0, 0); sb.o1 = __builtin_amdgcn_mfma_f32_32x32x16_bf16(f.v[2], pb0, sb.o1, 0, 0, 0);
;       sb.o0 = __builtin_amdgcn_mfma_f32_32x32x16_bf16(f.v[1], pb1, sb.o0, 0, 0, 0); sb.o1 = __builtin_amdgcn_mfma_f32_32x32x16_bf16(f.v[3], pb1, sb.o1, 0, 0, 0); }
.LBB0_675:
	s_cmp_lg_u32 s12, 0
	s_cselect_b64 s[14:15], -1, 0
	s_and_b64 vcc, s[14:15], s[8:9]
	s_add_i32 s13, s13, 32
	s_cmpk_lg_i32 s12, 0x480
	s_cselect_b32 s8, s13, 0xa0
	s_add_i32 s8, s8, s11
	s_cmpk_lt_u32 s8, 0x4000
	s_cselect_b32 s8, s8, s11
	v_or_b32_e32 v64, s8, v185
	v_mul_lo_u32 v64, v64, s67
	v_add_lshl_u32 v219, v64, v192, 1
	v_mov_b32_e32 v218, s53
	v_cndmask_b32_e32 v226, v218, v197, vcc
	v_mfma_f32_32x32x16_bf16 v[64:79], v[124:127], v[88:91], 0
	v_sub_f32_e32 v124, v199, v196
	v_exp_f32_e32 v199, v124
	v_sub_f32_e32 v124, v198, v196
	v_exp_f32_e32 v198, v124
	v_sub_f32_e32 v124, v201, v196
	v_exp_f32_e32 v201, v124
	v_sub_f32_e32 v124, v200, v196
	v_mfma_f32_32x32x16_bf16 v[64:79], v[120:123], v[92:95], v[64:79]
	v_sub_f32_e32 v120, v203, v196
	v_exp_f32_e32 v203, v120
	v_sub_f32_e32 v120, v202, v196
	v_exp_f32_e32 v202, v120
	v_sub_f32_e32 v120, v205, v196
	v_exp_f32_e32 v200, v124
	v_exp_f32_e32 v205, v120
	v_mfma_f32_32x32x16_bf16 v[64:79], v[116:119], v[104:107], v[64:79]
	v_sub_f32_e32 v116, v204, v196
	v_exp_f32_e32 v204, v116
	v_sub_f32_e32 v116, v207, v196
	v_exp_f32_e32 v207, v116
	v_sub_f32_e32 v116, v206, v196
	v_exp_f32_e32 v206, v116
	v_sub_f32_e32 v116, v211, v196
	v_exp_f32_e32 v211, v116
	v_sub_f32_e32 v116, v209, v196
	v_exp_f32_e32 v209, v116
	v_sub_f32_e32 v116, v208, v196
	v_mfma_f32_32x32x16_bf16 v[64:79], v[112:115], v[108:111], v[64:79]
	v_sub_f32_e32 v112, v210, v196
	v_exp_f32_e32 v208, v116
	v_sub_f32_e32 v116, v213, v196
	v_exp_f32_e32 v210, v112
	v_cvt_pk_bf16_f32 v112, v199, v198
	v_cvt_pk_bf16_f32 v113, v201, v200
	v_cvt_pk_bf16_f32 v114, v203, v202
	v_cvt_pk_bf16_f32 v115, v205, v204
	v_exp_f32_e32 v213, v116
	v_sub_f32_e32 v116, v212, v196
	s_waitcnt vmcnt(0)
	v_mfma_f32_32x32x16_bf16 v[48:63], v[140:143], v[112:115], v[48:63]
	v_exp_f32_e32 v212, v116
	global_load_dwordx4 v[124:127], v219, s[74:75]
	global_load_dwordx4 v[120:123], v219, s[74:75] offset:32
	v_cvt_pk_bf16_f32 v214, v207, v206
	v_cvt_pk_bf16_f32 v215, v211, v210
	v_cvt_pk_bf16_f32 v216, v209, v208
	v_cvt_pk_bf16_f32 v217, v213, v212
	v_mfma_f32_32x32x16_bf16 v[32:47], v[136:139], v[112:115], v[32:47]
	global_load_dwordx4 v[116:119], v219, s[74:75] offset:64
	global_load_dwordx4 v[112:115], v219, s[74:75] offset:96
	ds_read2_b32 v[220:221], v226 offset1:1
	s_waitcnt lgkmcnt(0)
	v_add_f32_e32 v219, v64, v220
	v_mfma_f32_32x32x16_bf16 v[48:63], v[132:135], v[214:217], v[48:63]
	v_add_f32_e32 v218, v65, v221
	v_max3_f32 v64, v219, s2, v218
	v_mfma_f32_32x32x16_bf16 v[32:47], v[128:131], v[214:217], v[32:47]
	ds_read2_b32 v[214:215], v226 offset0:2 offset1:3
	ds_read2_b32 v[222:223], v226 offset0:4 offset1:5
	ds_read2_b32 v[224:225], v226 offset0:6 offset1:7
	s_waitcnt lgkmcnt(2)
	v_add_f32_e32 v216, v66, v214
	v_add_f32_e32 v215, v67, v215
	v_max3_f32 v64, v64, v216, v215
	s_waitcnt lgkmcnt(1)
	v_add_f32_e32 v214, v68, v222
	v_add_f32_e32 v197, v69, v223
	v_max3_f32 v66, v64, v214, v197
	ds_read2_b32 v[64:65], v226 offset0:16 offset1:17
	s_waitcnt lgkmcnt(1)
	v_add_f32_e32 v69, v70, v224
	v_add_f32_e32 v68, v71, v225
	v_max3_f32 v70, v66, v69, v68
	ds_read2_b32 v[66:67], v226 offset0:18 offset1:19
	ds_read2_b32 v[220:221], v226 offset0:20 offset1:21
	ds_read2_b32 v[222:223], v226 offset0:22 offset1:23
	s_waitcnt lgkmcnt(3)
	v_add_f32_e32 v217, v72, v64
	v_add_f32_e32 v72, v73, v65
	v_max3_f32 v64, v70, v217, v72
	s_waitcnt lgkmcnt(2)
	v_add_f32_e32 v71, v74, v66
	v_add_f32_e32 v70, v75, v67
	v_max3_f32 v64, v64, v71, v70
	s_waitcnt lgkmcnt(1)
	v_add_f32_e32 v67, v76, v220
	v_add_f32_e32 v65, v77, v221
	v_max3_f32 v73, v64, v67, v65
	s_waitcnt lgkmcnt(0)
	v_add_f32_e32 v66, v78, v222
	v_add_f32_e32 v64, v79, v223
	v_max3_f32 v73, v73, v66, v64
	v_mov_b32_e32 v74, v73
	s_nop 1
	v_permlane32_swap_b32_e32 v73, v74
	v_max_f32_e32 v74, v74, v74
	v_max_f32_e32 v73, v73, v73
	v_max_f32_e32 v73, v73, v74
	v_cmp_gt_f32_e32 vcc, v73, v191
	s_cbranch_vccz .LBB0_672
	v_max_f32_e32 v73, v73, v73
	v_max_f32_e32 v74, v191, v191
	v_max_f32_e32 v73, v74, v73
	v_sub_f32_e32 v74, v191, v73
	v_exp_f32_e32 v74, v74
	v_mov_b32_e32 v191, v73
	v_mul_f32_e32 v190, v190, v74
	v_pk_mul_f32 v[30:31], v[30:31], v[74:75] op_sel_hi:[1,0]
	v_pk_mul_f32 v[28:29], v[28:29], v[74:75] op_sel_hi:[1,0]
	v_pk_mul_f32 v[26:27], v[26:27], v[74:75] op_sel_hi:[1,0]
	v_pk_mul_f32 v[24:25], v[24:25], v[74:75] op_sel_hi:[1,0]
	v_pk_mul_f32 v[22:23], v[22:23], v[74:75] op_sel_hi:[1,0]
	v_pk_mul_f32 v[20:21], v[20:21], v[74:75] op_sel_hi:[1,0]
	v_pk_mul_f32 v[18:19], v[18:19], v[74:75] op_sel_hi:[1,0]
	v_pk_mul_f32 v[16:17], v[16:17], v[74:75] op_sel_hi:[1,0]
	v_pk_mul_f32 v[14:15], v[14:15], v[74:75] op_sel_hi:[1,0]
	v_pk_mul_f32 v[12:13], v[12:13], v[74:75] op_sel_hi:[1,0]
	v_pk_mul_f32 v[10:11], v[10:11], v[74:75] op_sel_hi:[1,0]
	v_pk_mul_f32 v[8:9], v[8:9], v[74:75] op_sel_hi:[1,0]
	v_pk_mul_f32 v[6:7], v[6:7], v[74:75] op_sel_hi:[1,0]
	v_pk_mul_f32 v[4:5], v[4:5], v[74:75] op_sel_hi:[1,0]
	v_pk_mul_f32 v[2:3], v[2:3], v[74:75] op_sel_hi:[1,0]
	v_pk_mul_f32 v[0:1], v[0:1], v[74:75] op_sel_hi:[1,0]
	s_branch .LBB0_672

; template <class MB> __device__ __forceinline__ void la_soft(LA& st, f32x16& s, const TP& t, bf16x8& pf0, bf16x8& pf1) {
;     float mx = NEGBIG;
; #pragma unroll
;     for (int r = 0; r < 16; ++r) { s[r] = MB::apply(t, r, s[r]); mx = __builtin_fmaxf(mx, s[r]); }
;     { auto rr = __builtin_amdgcn_permlane32_swap(__float_as_uint(mx), __float_as_uint(mx), false, false); mx = __builtin_fmaxf(__uint_as_float(rr[0]), __uint_as_float(rr[1])); }
;     if (__any(mx > st.m)) { const float mn = __builtin_fmaxf(st.m, mx), alpha = __builtin_amdgcn_exp2f(st.m - mn); st.m = mn; st.l *= alpha; st.o0 *= alpha; st.o1 *= alpha; }
; template <class MB, int V1, class VS> __device__ __forceinline__ void la_step2(LA& sa, LA& sb, const bf16x8 (&qa)[4], const bf16x8 (&qb)[4], Frag& f, const char* kb, const VS& vs, const TP& t, const TP& n) {
;     bf16x8 pa0, pa1;
;     { f32x16 s0 = zero16();
; #pragma unroll
;       for (int d0 = 0; d0 < 4; ++d0) s0 = __builtin_amdgcn_mfma_f32_32x32x16_bf16(f.k[d0], qa[d0], s0, 0, 0, 0);
;       la_soft<MB>(sa, s0, t, pa0, pa1); }
.LBB0_678:
	v_lshl_add_u32 v64, s41, 2, v165
	v_ashrrev_i32_e32 v65, 31, v64
	v_lshl_add_u64 v[64:65], s[56:57], 0, v[64:65]
	v_add_co_u32_e32 v66, vcc, s80, v64
	s_cmp_eq_u32 s60, 8
	s_nop 0
	v_addc_co_u32_e32 v67, vcc, 0, v65, vcc
	global_load_dwordx4 v[128:131], v[66:67], off offset:2080
	global_load_dwordx4 v[136:139], v[66:67], off offset:2048
	global_load_dwordx4 v[132:135], v[64:65], off offset:32
	global_load_dwordx4 v[140:143], v[64:65], off
	s_cselect_b64 s[40:41], -1, 0
	v_add_u32_e32 v166, 0x200, v167
	v_mov_b32_e32 v64, s53
	v_cndmask_b32_e64 v183, v166, v64, s[40:41]
	ds_read2_b32 v[168:169], v183 offset1:1
	ds_read2_b32 v[234:235], v183 offset0:2 offset1:3
	ds_read2_b32 v[236:237], v183 offset0:4 offset1:5
	ds_read2_b32 v[238:239], v183 offset0:6 offset1:7
	ds_read2_b32 v[240:241], v183 offset0:16 offset1:17
	ds_read2_b32 v[242:243], v183 offset0:18 offset1:19
	ds_read2_b32 v[244:245], v183 offset0:20 offset1:21
	ds_read2_b32 v[246:247], v183 offset0:22 offset1:23
	s_waitcnt vmcnt(7)
	v_mfma_f32_32x32x16_bf16 v[64:79], v[124:127], v[96:99], 0
	s_waitcnt vmcnt(6)
	v_mfma_f32_32x32x16_bf16 v[64:79], v[120:123], v[100:103], v[64:79]
	s_waitcnt vmcnt(5)
	v_mfma_f32_32x32x16_bf16 v[64:79], v[116:119], v[104:107], v[64:79]
	s_waitcnt vmcnt(4)
	v_mfma_f32_32x32x16_bf16 v[64:79], v[112:115], v[108:111], v[64:79]
	s_waitcnt lgkmcnt(0)
	s_nop 10
	v_add_f32_e32 v64, v64, v168
	v_cndmask_b32_e64 v168, v232, v64, s[6:7]
	v_add_f32_e32 v64, v65, v169
	v_cndmask_b32_e64 v169, v232, v64, s[8:9]
	v_max3_f32 v172, v168, s2, v169
	v_add_f32_e32 v64, v66, v234
	v_cndmask_b32_e64 v170, v232, v64, s[10:11]
	v_add_f32_e32 v64, v67, v235
	v_cndmask_b32_e64 v171, v232, v64, s[12:13]
	v_max3_f32 v66, v172, v170, v171
	v_add_f32_e32 v64, v68, v236
	v_cndmask_b32_e64 v172, v232, v64, s[14:15]
	v_add_f32_e32 v64, v69, v237
	v_cndmask_b32_e64 v173, v232, v64, s[16:17]
	v_max3_f32 v66, v66, v172, v173
	v_add_f32_e32 v64, v70, v238
	v_cndmask_b32_e64 v175, v232, v64, s[18:19]
	v_add_f32_e32 v64, v71, v239
	v_cndmask_b32_e64 v174, v232, v64, s[20:21]
	v_max3_f32 v66, v66, v175, v174
	v_add_f32_e32 v64, v72, v240
	v_cndmask_b32_e64 v176, v232, v64, s[22:23]
	v_add_f32_e32 v64, v73, v241
	v_cndmask_b32_e64 v177, v232, v64, s[24:25]
	v_max3_f32 v66, v66, v176, v177
	v_add_f32_e32 v64, v74, v242
	v_cndmask_b32_e64 v179, v232, v64, s[26:27]
	v_add_f32_e32 v64, v75, v243
	v_cndmask_b32_e64 v178, v232, v64, s[28:29]
	v_max3_f32 v66, v66, v179, v178
	v_add_f32_e32 v64, v76, v244
	v_cndmask_b32_e64 v180, v232, v64, s[30:31]
	v_add_f32_e32 v64, v77, v245
	v_cndmask_b32_e64 v182, v232, v64, s[34:35]
	v_max3_f32 v66, v66, v180, v182
	v_add_f32_e32 v64, v78, v246
	v_cndmask_b32_e64 v183, v232, v64, s[36:37]
	v_add_f32_e32 v64, v79, v247
	v_cndmask_b32_e64 v190, v232, v64, s[38:39]
	v_max3_f32 v64, v66, v183, v190
	v_mov_b32_e32 v65, v64
	s_nop 1
	v_permlane32_swap_b32_e32 v64, v65
	v_max_f32_e32 v65, v65, v65
	v_max_f32_e32 v64, v64, v64
	v_max_f32_e32 v64, v64, v65
	v_cmp_gt_f32_e32 vcc, v64, v162
	s_cbranch_vccz .LBB0_680
	v_max_f32_e32 v64, v64, v64
	v_max_f32_e32 v65, v162, v162
	v_max_f32_e32 v65, v65, v64
	v_sub_f32_e32 v64, v162, v65
	v_exp_f32_e32 v64, v64
	v_mov_b32_e32 v162, v65
	v_mul_f32_e32 v157, v157, v64
	v_pk_mul_f32 v[62:63], v[62:63], v[64:65] op_sel_hi:[1,0]
	v_pk_mul_f32 v[60:61], v[60:61], v[64:65] op_sel_hi:[1,0]
	v_pk_mul_f32 v[58:59], v[58:59], v[64:65] op_sel_hi:[1,0]
	v_pk_mul_f32 v[56:57], v[56:57], v[64:65] op_sel_hi:[1,0]
	v_pk_mul_f32 v[54:55], v[54:55], v[64:65] op_sel_hi:[1,0]
	v_pk_mul_f32 v[52:53], v[52:53], v[64:65] op_sel_hi:[1,0]
	v_pk_mul_f32 v[50:51], v[50:51], v[64:65] op_sel_hi:[1,0]
	v_pk_mul_f32 v[48:49], v[48:49], v[64:65] op_sel_hi:[1,0]
	v_pk_mul_f32 v[46:47], v[46:47], v[64:65] op_sel_hi:[1,0]
	v_pk_mul_f32 v[44:45], v[44:45], v[64:65] op_sel_hi:[1,0]
	v_pk_mul_f32 v[42:43], v[42:43], v[64:65] op_sel_hi:[1,0]
	v_pk_mul_f32 v[40:41], v[40:41], v[64:65] op_sel_hi:[1,0]
	v_pk_mul_f32 v[38:39], v[38:39], v[64:65] op_sel_hi:[1,0]
	v_pk_mul_f32 v[36:37], v[36:37], v[64:65] op_sel_hi:[1,0]
	v_pk_mul_f32 v[34:35], v[34:35], v[64:65] op_sel_hi:[1,0]
	v_pk_mul_f32 v[32:33], v[32:33], v[64:65] op_sel_hi:[1,0]
; __device__ __forceinline__ unsigned cvt_pk_bf16(float lo, float hi) { f32x2_c v = {lo, hi}; bf16x2_c b = __builtin_convertvector(v, bf16x2_c); return __builtin_bit_cast(unsigned, b); }
; template <class MB> __device__ __forceinline__ void la_soft(LA& st, f32x16& s, const TP& t, bf16x8& pf0, bf16x8& pf1) {
;     ...
;     float rs = 0.f;
; #pragma unroll
;     for (int r = 0; r < 16; ++r) { s[r] = __builtin_amdgcn_exp2f(s[r] - st.m); rs += s[r]; }
;     st.l += rs;
;     u32x4 p0, p1;
; #pragma unroll
;     for (int e = 0; e < 4; ++e) { p0[e] = cvt_pk_bf16(s[2 * e], s[2 * e + 1]); p1[e] = cvt_pk_bf16(s[8 + 2 * e], s[8 + 2 * e + 1]); }
;     pf0 = __builtin_bit_cast(bf16x8, p0); pf1 = __builtin_bit_cast(bf16x8, p1);
; }
; template <class MB, int V1, class VS> __device__ __forceinline__ void la_step2(LA& sa, LA& sb, const bf16x8 (&qa)[4], const bf16x8 (&qb)[4], Frag& f, const char* kb, const VS& vs, const TP& t, const TP& n) {
;     bf16x8 pa0, pa1;
;     { f32x16 s0 = zero16();
; #pragma unroll
;       for (int d0 = 0; d0 < 4; ++d0) s0 = __builtin_amdgcn_mfma_f32_32x32x16_bf16(f.k[d0], qa[d0], s0, 0, 0, 0);
;       la_soft<MB>(sa, s0, t, pa0, pa1); }
;     f32x16 s1 = zero16();
; #pragma unroll
;     for (int d0 = 0; d0 < 4; ++d0) s1 = __builtin_amdgcn_mfma_f32_32x32x16_bf16(f.k[d0], qb[d0], s1, 0, 0, 0);
;     la_loadK(f, kb, n);
;     sa.o0 = __builtin_amdgcn_mfma_f32_32x32x16_bf16(f.v[0], pa0, sa.o0, 0, 0, 0); sa.o1 = __builtin_amdgcn_mfma_f32_32x32x16_bf16(f.v[2], pa0, sa.o1, 0, 0, 0);
;     sa.o0 = __builtin_amdgcn_mfma_f32_32x32x16_bf16(f.v[1], pa1, sa.o0, 0, 0, 0); sa.o1 = __builtin_amdgcn_mfma_f32_32x32x16_bf16(f.v[3], pa1, sa.o1, 0, 0, 0);
;     { bf16x8 pb0, pb1; const TP tb = MB::second(t);
;       la_soft<MB>(sb, s1, tb, pb0, pb1);
;       sb.o0 = __builtin_amdgcn_mfma_f32_32x32x16_bf16(f.v[0], pb0, sb.o0, 0, 0, 0); sb.o1 = __builtin_amdgcn_mfma_f32_32x32x16_bf16(f.v[2], pb0, sb.o1, 0, 0, 0);
;       sb.o0 = __builtin_amdgcn_mfma_f32_32x32x16_bf16(f.v[1], pb1, sb.o0, 0, 0, 0); sb.o1 = __builtin_amdgcn_mfma_f32_32x32x16_bf16(f.v[3], pb1, sb.o1, 0, 0, 0); }
.LBB0_680:
	s_add_i32 s0, s59, s60
	v_cmp_ge_u32_e32 vcc, s0, v159
	v_cmp_lt_u32_e64 s[44:45], s0, v153
	s_and_b64 vcc, vcc, s[44:45]
	s_add_i32 s60, s60, 1
	s_and_b64 s[40:41], s[40:41], exec
	s_cselect_b32 s0, 8, s60
	s_add_i32 s0, s0, s59
	s_min_i32 s0, s0, 0xff
	s_lshl_b32 s0, s0, 6
	s_or_b32 s41, s0, s55
	v_or_b32_e32 v64, s41, v185
	v_mul_lo_u32 v64, v64, s67
	v_add_lshl_u32 v196, v64, v161, 1
	v_mov_b32_e32 v191, s53
	v_cndmask_b32_e32 v204, v191, v167, vcc
	v_mfma_f32_32x32x16_bf16 v[64:79], v[124:127], v[80:83], 0
	v_sub_f32_e32 v124, v168, v162
	v_exp_f32_e32 v168, v124
	v_sub_f32_e32 v124, v169, v162
	v_exp_f32_e32 v169, v124
	v_sub_f32_e32 v124, v170, v162
	v_exp_f32_e32 v170, v124
	v_sub_f32_e32 v124, v171, v162
	v_mfma_f32_32x32x16_bf16 v[64:79], v[120:123], v[84:87], v[64:79]
	v_sub_f32_e32 v120, v172, v162
	v_exp_f32_e32 v172, v120
	v_sub_f32_e32 v120, v173, v162
	v_exp_f32_e32 v173, v120
	v_sub_f32_e32 v120, v175, v162
	v_exp_f32_e32 v171, v124
	v_exp_f32_e32 v175, v120
	v_mfma_f32_32x32x16_bf16 v[64:79], v[116:119], v[88:91], v[64:79]
	v_sub_f32_e32 v116, v174, v162
	v_exp_f32_e32 v174, v116
	v_sub_f32_e32 v116, v176, v162
	v_exp_f32_e32 v176, v116
	v_sub_f32_e32 v116, v177, v162
	v_exp_f32_e32 v177, v116
	v_sub_f32_e32 v116, v179, v162
	v_exp_f32_e32 v179, v116
	v_sub_f32_e32 v116, v180, v162
	v_exp_f32_e32 v180, v116
	v_sub_f32_e32 v116, v182, v162
	v_mfma_f32_32x32x16_bf16 v[64:79], v[112:115], v[92:95], v[64:79]
	v_sub_f32_e32 v112, v178, v162
	v_exp_f32_e32 v182, v116
	v_sub_f32_e32 v116, v183, v162
	v_exp_f32_e32 v178, v112
	v_cvt_pk_bf16_f32 v112, v168, v169
	v_cvt_pk_bf16_f32 v113, v170, v171
	v_cvt_pk_bf16_f32 v114, v172, v173
	v_cvt_pk_bf16_f32 v115, v175, v174
	v_exp_f32_e32 v183, v116
	v_sub_f32_e32 v116, v190, v162
	s_waitcnt vmcnt(0)
	v_mfma_f32_32x32x16_bf16 v[48:63], v[140:143], v[112:115], v[48:63]
	v_exp_f32_e32 v190, v116
	global_load_dwordx4 v[124:127], v196, s[74:75]
	global_load_dwordx4 v[120:123], v196, s[74:75] offset:32
	v_cvt_pk_bf16_f32 v192, v176, v177
	v_cvt_pk_bf16_f32 v193, v179, v178
	v_cvt_pk_bf16_f32 v194, v180, v182
	v_cvt_pk_bf16_f32 v195, v183, v190
	v_mfma_f32_32x32x16_bf16 v[32:47], v[136:139], v[112:115], v[32:47]
	global_load_dwordx4 v[116:119], v196, s[74:75] offset:64
	global_load_dwordx4 v[112:115], v196, s[74:75] offset:96
	ds_read2_b32 v[196:197], v204 offset1:1
	ds_read2_b32 v[198:199], v204 offset0:2 offset1:3
	ds_read2_b32 v[200:201], v204 offset0:4 offset1:5
	ds_read2_b32 v[202:203], v204 offset0:6 offset1:7
	s_waitcnt lgkmcnt(3)
	v_add_f32_e32 v64, v64, v196
	v_mfma_f32_32x32x16_bf16 v[48:63], v[132:135], v[192:195], v[48:63]
	v_mfma_f32_32x32x16_bf16 v[32:47], v[128:131], v[192:195], v[32:47]
	v_cndmask_b32_e64 v195, v232, v64, s[6:7]
	v_add_f32_e32 v64, v65, v197
	s_waitcnt lgkmcnt(2)
	v_add_f32_e32 v65, v66, v198
	v_cndmask_b32_e64 v194, v232, v65, s[10:11]
	v_add_f32_e32 v65, v67, v199
	v_cndmask_b32_e64 v193, v232, v64, s[8:9]
	v_cndmask_b32_e64 v191, v232, v65, s[12:13]
	s_waitcnt lgkmcnt(1)
	v_add_f32_e32 v65, v68, v200
	v_max3_f32 v64, v195, s2, v193
	v_cndmask_b32_e64 v192, v232, v65, s[14:15]
	v_add_f32_e32 v65, v69, v201
	v_max3_f32 v64, v64, v194, v191
	v_cndmask_b32_e64 v167, v232, v65, s[16:17]
	v_max3_f32 v66, v64, v192, v167
	s_waitcnt lgkmcnt(0)
	v_add_f32_e32 v64, v70, v202
	v_cndmask_b32_e64 v70, v232, v64, s[18:19]
	v_add_f32_e32 v64, v71, v203
	v_cndmask_b32_e64 v69, v232, v64, s[20:21]
	ds_read2_b32 v[64:65], v204 offset0:16 offset1:17
	v_max3_f32 v68, v66, v70, v69
	ds_read2_b32 v[66:67], v204 offset0:18 offset1:19
	ds_read2_b32 v[198:199], v204 offset0:20 offset1:21
	ds_read2_b32 v[200:201], v204 offset0:22 offset1:23
	s_waitcnt lgkmcnt(3)
	v_add_f32_e32 v64, v72, v64
	v_cndmask_b32_e64 v196, v232, v64, s[22:23]
	v_add_f32_e32 v64, v73, v65
	v_cndmask_b32_e64 v71, v232, v64, s[24:25]
	s_waitcnt lgkmcnt(2)
	v_add_f32_e32 v64, v74, v66
	v_cndmask_b32_e64 v72, v232, v64, s[26:27]
	v_add_f32_e32 v64, v75, v67
	v_max3_f32 v65, v68, v196, v71
	v_cndmask_b32_e64 v64, v232, v64, s[28:29]
	s_waitcnt lgkmcnt(1)
	v_add_f32_e32 v66, v76, v198
	v_add_f32_e32 v67, v77, v199
	v_max3_f32 v65, v65, v72, v64
	v_cndmask_b32_e64 v66, v232, v66, s[30:31]
	v_cndmask_b32_e64 v67, v232, v67, s[34:35]
	v_max3_f32 v73, v65, v66, v67
	s_waitcnt lgkmcnt(0)
	v_add_f32_e32 v65, v78, v200
	v_cndmask_b32_e64 v68, v232, v65, s[36:37]
	v_add_f32_e32 v65, v79, v201
	v_cndmask_b32_e64 v65, v232, v65, s[38:39]
	v_max3_f32 v73, v73, v68, v65
	v_mov_b32_e32 v74, v73
	s_nop 1
	v_permlane32_swap_b32_e32 v73, v74
	v_max_f32_e32 v74, v74, v74
	v_max_f32_e32 v73, v73, v73
	v_max_f32_e32 v73, v73, v74
	v_cmp_gt_f32_e32 vcc, v73, v145
	s_cbranch_vccz .LBB0_682
	v_max_f32_e32 v73, v73, v73
	v_max_f32_e32 v74, v145, v145
	v_max_f32_e32 v73, v74, v73
	v_sub_f32_e32 v74, v145, v73
	v_exp_f32_e32 v74, v74
	v_mov_b32_e32 v145, v73
	v_mul_f32_e32 v156, v156, v74
	v_pk_mul_f32 v[30:31], v[30:31], v[74:75] op_sel_hi:[1,0]
	v_pk_mul_f32 v[28:29], v[28:29], v[74:75] op_sel_hi:[1,0]
	v_pk_mul_f32 v[26:27], v[26:27], v[74:75] op_sel_hi:[1,0]
	v_pk_mul_f32 v[24:25], v[24:25], v[74:75] op_sel_hi:[1,0]
	v_pk_mul_f32 v[22:23], v[22:23], v[74:75] op_sel_hi:[1,0]
	v_pk_mul_f32 v[20:21], v[20:21], v[74:75] op_sel_hi:[1,0]
	v_pk_mul_f32 v[18:19], v[18:19], v[74:75] op_sel_hi:[1,0]
	v_pk_mul_f32 v[16:17], v[16:17], v[74:75] op_sel_hi:[1,0]
	v_pk_mul_f32 v[14:15], v[14:15], v[74:75] op_sel_hi:[1,0]
	v_pk_mul_f32 v[12:13], v[12:13], v[74:75] op_sel_hi:[1,0]
	v_pk_mul_f32 v[10:11], v[10:11], v[74:75] op_sel_hi:[1,0]
	v_pk_mul_f32 v[8:9], v[8:9], v[74:75] op_sel_hi:[1,0]
	v_pk_mul_f32 v[6:7], v[6:7], v[74:75] op_sel_hi:[1,0]
	v_pk_mul_f32 v[4:5], v[4:5], v[74:75] op_sel_hi:[1,0]
	v_pk_mul_f32 v[2:3], v[2:3], v[74:75] op_sel_hi:[1,0]
	v_pk_mul_f32 v[0:1], v[0:1], v[74:75] op_sel_hi:[1,0]

; template <class MB, int V1, class VS> __device__ __forceinline__ void la_step(LA& st, const bf16x8 (&qf)[4], Frag& f, const char* kb, const VS& vs, const TP& t, const TP& n) {
;     f32x16 s = zero16();
; #pragma unroll
;     for (int d0 = 0; d0 < 4; ++d0) s = __builtin_amdgcn_mfma_f32_32x32x16_bf16(f.k[d0], qf[d0], s, 0, 0, 0);
;     la_loadK(f, kb, n);
;     float mx = NEGBIG;
; #pragma unroll
;     for (int r = 0; r < 16; ++r) { s[r] = MB::apply(t, r, s[r]); mx = __builtin_fmaxf(mx, s[r]); }
;     { auto rr = __builtin_amdgcn_permlane32_swap(__float_as_uint(mx), __float_as_uint(mx), false, false); mx = __builtin_fmaxf(__uint_as_float(rr[0]), __uint_as_float(rr[1])); }
;     if (__any(mx > st.m)) { const float mn = __builtin_fmaxf(st.m, mx), alpha = __builtin_amdgcn_exp2f(st.m - mn); st.m = mn; st.l *= alpha; st.o0 *= alpha; st.o1 *= alpha; }
;     float rs = 0.f;
; #pragma unroll
;     for (int r = 0; r < 16; ++r) { s[r] = __builtin_amdgcn_exp2f(s[r] - st.m); rs += s[r]; }
.LBB0_685:
	v_or_b32_e32 v64, v64, v184
	v_lshl_or_b32 v64, v64, 7, s0
	v_add_lshl_u32 v64, v64, v164, 1
	v_ashrrev_i32_e32 v65, 31, v64
	v_lshl_add_u64 v[64:65], s[56:57], 0, v[64:65]
	v_add_co_u32_e32 v66, vcc, s80, v64
	v_add_u32_e32 v170, s24, v166
	s_nop 0
	v_addc_co_u32_e32 v67, vcc, 0, v65, vcc
	global_load_dwordx4 v[128:131], v[66:67], off offset:2560
	global_load_dwordx4 v[132:135], v[66:67], off offset:2048
	global_load_dwordx4 v[136:139], v[64:65], off offset:512
	global_load_dwordx4 v[140:143], v[64:65], off
	v_add_u32_e32 v167, 0x7120, v170
	s_waitcnt vmcnt(7)
	v_mfma_f32_32x32x16_bf16 v[64:79], v[112:115], v[96:99], 0
	s_waitcnt vmcnt(6)
	v_mfma_f32_32x32x16_bf16 v[64:79], v[120:123], v[100:103], v[64:79]
	s_waitcnt vmcnt(5)
	v_mfma_f32_32x32x16_bf16 v[64:79], v[116:119], v[104:107], v[64:79]
	s_waitcnt vmcnt(4)
	v_mfma_f32_32x32x16_bf16 v[64:79], v[124:127], v[108:111], v[64:79]
	global_load_dwordx4 v[112:115], v[152:153], off
	global_load_dwordx4 v[120:123], v[152:153], off offset:32
	global_load_dwordx4 v[116:119], v[152:153], off offset:64
	global_load_dwordx4 v[124:127], v[152:153], off offset:96
	ds_read2_b32 v[168:169], v167 offset1:1
	s_waitcnt lgkmcnt(0)
	s_nop 5
	v_add_f32_e32 v64, v64, v168
	v_cndmask_b32_e64 v167, v232, v64, s[6:7]
	v_add_f32_e32 v64, v65, v169
	v_add_u32_e32 v65, 0x7128, v170
	ds_read2_b32 v[168:169], v65 offset1:1
	v_cndmask_b32_e64 v64, v232, v64, s[8:9]
	v_max3_f32 v171, v167, s2, v64
	s_waitcnt lgkmcnt(0)
	v_add_f32_e32 v65, v66, v168
	v_cndmask_b32_e64 v66, v232, v65, s[10:11]
	v_add_f32_e32 v65, v67, v169
	v_add_u32_e32 v67, 0x7130, v170
	ds_read2_b32 v[168:169], v67 offset1:1
	v_cndmask_b32_e64 v65, v232, v65, s[12:13]
	v_max3_f32 v171, v171, v66, v65
	s_waitcnt lgkmcnt(0)
	v_add_f32_e32 v67, v68, v168
	v_cndmask_b32_e64 v68, v232, v67, s[14:15]
	v_add_f32_e32 v67, v69, v169
	v_add_u32_e32 v69, 0x7138, v170
	ds_read2_b32 v[168:169], v69 offset1:1
	v_cndmask_b32_e64 v67, v232, v67, s[16:17]
	v_max3_f32 v171, v171, v68, v67
	s_waitcnt lgkmcnt(0)
	v_add_f32_e32 v69, v70, v168
	v_cndmask_b32_e64 v70, v232, v69, s[18:19]
	v_add_f32_e32 v69, v71, v169
	v_add_u32_e32 v71, 0x7520, v170
	ds_read2_b32 v[168:169], v71 offset1:1
	v_cndmask_b32_e64 v69, v232, v69, s[20:21]
	v_max3_f32 v171, v171, v70, v69
	s_waitcnt lgkmcnt(0)
	v_add_f32_e32 v71, v72, v168
	v_cndmask_b32_e64 v72, v232, v71, s[6:7]
	v_add_f32_e32 v71, v73, v169
	v_add_u32_e32 v73, 0x7528, v170
	ds_read2_b32 v[168:169], v73 offset1:1
	v_cndmask_b32_e64 v71, v232, v71, s[8:9]
	v_max3_f32 v171, v171, v72, v71
	s_waitcnt lgkmcnt(0)
	v_add_f32_e32 v73, v74, v168
	v_cndmask_b32_e64 v74, v232, v73, s[10:11]
	v_add_f32_e32 v73, v75, v169
	v_add_u32_e32 v75, 0x7530, v170
	ds_read2_b32 v[168:169], v75 offset1:1
	v_cndmask_b32_e64 v73, v232, v73, s[12:13]
	v_max3_f32 v171, v171, v74, v73
	s_waitcnt lgkmcnt(0)
	v_add_f32_e32 v75, v76, v168
	v_cndmask_b32_e64 v76, v232, v75, s[14:15]
	v_add_f32_e32 v75, v77, v169
	v_add_u32_e32 v77, 0x7538, v170
	ds_read2_b32 v[168:169], v77 offset1:1
	v_cndmask_b32_e64 v75, v232, v75, s[16:17]
	v_max3_f32 v171, v171, v76, v75
	s_waitcnt lgkmcnt(0)
	v_add_f32_e32 v77, v78, v168
	v_cndmask_b32_e64 v78, v232, v77, s[18:19]
	v_add_f32_e32 v77, v79, v169
	v_cndmask_b32_e64 v77, v232, v77, s[20:21]
	v_max3_f32 v79, v171, v78, v77
	v_mov_b32_e32 v168, v79
	s_nop 1
	v_permlane32_swap_b32_e32 v79, v168
	v_max_f32_e32 v168, v168, v168
	v_max_f32_e32 v79, v79, v79
	v_max_f32_e32 v79, v79, v168
	v_cmp_gt_f32_e32 vcc, v79, v162
	s_cbranch_vccz .LBB0_687
	v_max_f32_e32 v79, v79, v79
	v_max_f32_e32 v168, v162, v162
	v_max_f32_e32 v79, v168, v79
	v_sub_f32_e32 v162, v162, v79
	v_exp_f32_e32 v162, v162
	s_nop 0
	v_mul_f32_e32 v157, v157, v162
	v_pk_mul_f32 v[62:63], v[62:63], v[162:163] op_sel_hi:[1,0]
	v_pk_mul_f32 v[60:61], v[60:61], v[162:163] op_sel_hi:[1,0]
	v_pk_mul_f32 v[58:59], v[58:59], v[162:163] op_sel_hi:[1,0]
	v_pk_mul_f32 v[56:57], v[56:57], v[162:163] op_sel_hi:[1,0]
	v_pk_mul_f32 v[54:55], v[54:55], v[162:163] op_sel_hi:[1,0]
	v_pk_mul_f32 v[52:53], v[52:53], v[162:163] op_sel_hi:[1,0]
	v_pk_mul_f32 v[50:51], v[50:51], v[162:163] op_sel_hi:[1,0]
	v_pk_mul_f32 v[48:49], v[48:49], v[162:163] op_sel_hi:[1,0]
	v_pk_mul_f32 v[46:47], v[46:47], v[162:163] op_sel_hi:[1,0]
	v_pk_mul_f32 v[44:45], v[44:45], v[162:163] op_sel_hi:[1,0]
	v_pk_mul_f32 v[42:43], v[42:43], v[162:163] op_sel_hi:[1,0]
	v_pk_mul_f32 v[40:41], v[40:41], v[162:163] op_sel_hi:[1,0]
	v_pk_mul_f32 v[38:39], v[38:39], v[162:163] op_sel_hi:[1,0]
	v_pk_mul_f32 v[36:37], v[36:37], v[162:163] op_sel_hi:[1,0]
	v_pk_mul_f32 v[34:35], v[34:35], v[162:163] op_sel_hi:[1,0]
	v_pk_mul_f32 v[32:33], v[32:33], v[162:163] op_sel_hi:[1,0]
	v_mov_b32_e32 v162, v79

; template <class MB, int V1, class VS> __device__ __forceinline__ void la_step(LA& st, const bf16x8 (&qf)[4], Frag& f, const char* kb, const VS& vs, const TP& t, const TP& n) {
;     f32x16 s = zero16();
; #pragma unroll
;     for (int d0 = 0; d0 < 4; ++d0) s = __builtin_amdgcn_mfma_f32_32x32x16_bf16(f.k[d0], qf[d0], s, 0, 0, 0);
;     la_loadK(f, kb, n);
;     float mx = NEGBIG;
; #pragma unroll
;     for (int r = 0; r < 16; ++r) { s[r] = MB::apply(t, r, s[r]); mx = __builtin_fmaxf(mx, s[r]); }
;     { auto rr = __builtin_amdgcn_permlane32_swap(__float_as_uint(mx), __float_as_uint(mx), false, false); mx = __builtin_fmaxf(__uint_as_float(rr[0]), __uint_as_float(rr[1])); }
;     if (__any(mx > st.m)) { const float mn = __builtin_fmaxf(st.m, mx), alpha = __builtin_amdgcn_exp2f(st.m - mn); st.m = mn; st.l *= alpha; st.o0 *= alpha; st.o1 *= alpha; }
;     float rs = 0.f;
; #pragma unroll
;     for (int r = 0; r < 16; ++r) { s[r] = __builtin_amdgcn_exp2f(s[r] - st.m); rs += s[r]; }
.LBB0_690:
	v_add_u32_e32 v64, v159, v184
	v_lshl_or_b32 v64, v64, 7, s0
	v_add_lshl_u32 v64, v64, v164, 1
	v_ashrrev_i32_e32 v65, 31, v64
	v_lshl_add_u64 v[64:65], s[56:57], 0, v[64:65]
	v_add_co_u32_e32 v66, vcc, s80, v64
	v_add_u32_e32 v136, s24, v131
	s_nop 0
	v_addc_co_u32_e32 v67, vcc, 0, v65, vcc
	global_load_dwordx4 v[112:115], v[66:67], off offset:2560
	global_load_dwordx4 v[116:119], v[66:67], off offset:2048
	global_load_dwordx4 v[120:123], v[64:65], off offset:512
	global_load_dwordx4 v[124:127], v[64:65], off
	v_add_u32_e32 v132, 0x7120, v136
	s_waitcnt vmcnt(7)
	v_mfma_f32_32x32x16_bf16 v[64:79], v[96:99], v[80:83], 0
	s_waitcnt vmcnt(6)
	v_mfma_f32_32x32x16_bf16 v[64:79], v[104:107], v[84:87], v[64:79]
	s_waitcnt vmcnt(5)
	v_mfma_f32_32x32x16_bf16 v[64:79], v[100:103], v[88:91], v[64:79]
	s_waitcnt vmcnt(4)
	v_mfma_f32_32x32x16_bf16 v[64:79], v[108:111], v[92:95], v[64:79]
	global_load_dwordx4 v[96:99], v[128:129], off
	global_load_dwordx4 v[104:107], v[128:129], off offset:32
	global_load_dwordx4 v[100:103], v[128:129], off offset:64
	global_load_dwordx4 v[108:111], v[128:129], off offset:96
	ds_read2_b32 v[132:133], v132 offset1:1
	s_waitcnt lgkmcnt(0)
	s_nop 5
	v_add_f32_e32 v64, v64, v132
	v_cndmask_b32_e64 v132, v232, v64, s[6:7]
	v_add_f32_e32 v64, v65, v133
	v_add_u32_e32 v65, 0x7128, v136
	ds_read2_b32 v[134:135], v65 offset1:1
	v_cndmask_b32_e64 v64, v232, v64, s[8:9]
	v_max3_f32 v133, v132, s2, v64
	s_waitcnt lgkmcnt(0)
	v_add_f32_e32 v65, v66, v134
	v_cndmask_b32_e64 v66, v232, v65, s[10:11]
	v_add_f32_e32 v65, v67, v135
	v_add_u32_e32 v67, 0x7130, v136
	ds_read2_b32 v[134:135], v67 offset1:1
	v_cndmask_b32_e64 v65, v232, v65, s[12:13]
	v_max3_f32 v133, v133, v66, v65
	s_waitcnt lgkmcnt(0)
	v_add_f32_e32 v67, v68, v134
	v_cndmask_b32_e64 v68, v232, v67, s[14:15]
	v_add_f32_e32 v67, v69, v135
	v_add_u32_e32 v69, 0x7138, v136
	ds_read2_b32 v[134:135], v69 offset1:1
	v_cndmask_b32_e64 v67, v232, v67, s[16:17]
	v_max3_f32 v133, v133, v68, v67
	s_waitcnt lgkmcnt(0)
	v_add_f32_e32 v69, v70, v134
	v_cndmask_b32_e64 v70, v232, v69, s[18:19]
	v_add_f32_e32 v69, v71, v135
	v_add_u32_e32 v71, 0x7520, v136
	ds_read2_b32 v[134:135], v71 offset1:1
	v_cndmask_b32_e64 v69, v232, v69, s[20:21]
	v_max3_f32 v133, v133, v70, v69
	s_waitcnt lgkmcnt(0)
	v_add_f32_e32 v71, v72, v134
	v_cndmask_b32_e64 v72, v232, v71, s[6:7]
	v_add_f32_e32 v71, v73, v135
	v_add_u32_e32 v73, 0x7528, v136
	ds_read2_b32 v[134:135], v73 offset1:1
	v_cndmask_b32_e64 v71, v232, v71, s[8:9]
	v_max3_f32 v133, v133, v72, v71
	s_waitcnt lgkmcnt(0)
	v_add_f32_e32 v73, v74, v134
	v_cndmask_b32_e64 v74, v232, v73, s[10:11]
	v_add_f32_e32 v73, v75, v135
	v_add_u32_e32 v75, 0x7530, v136
	ds_read2_b32 v[134:135], v75 offset1:1
	v_cndmask_b32_e64 v73, v232, v73, s[12:13]
	v_max3_f32 v133, v133, v74, v73
	s_waitcnt lgkmcnt(0)
	v_add_f32_e32 v75, v76, v134
	v_cndmask_b32_e64 v76, v232, v75, s[14:15]
	v_add_f32_e32 v75, v77, v135
	v_add_u32_e32 v77, 0x7538, v136
	ds_read2_b32 v[134:135], v77 offset1:1
	v_cndmask_b32_e64 v75, v232, v75, s[16:17]
	v_max3_f32 v133, v133, v76, v75
	s_waitcnt lgkmcnt(0)
	v_add_f32_e32 v77, v78, v134
	v_cndmask_b32_e64 v78, v232, v77, s[18:19]
	v_add_f32_e32 v77, v79, v135
	v_cndmask_b32_e64 v77, v232, v77, s[20:21]
	v_max3_f32 v79, v133, v78, v77
	v_mov_b32_e32 v133, v79
	s_nop 1
	v_permlane32_swap_b32_e32 v79, v133
	v_max_f32_e32 v133, v133, v133
	v_max_f32_e32 v79, v79, v79
	v_max_f32_e32 v79, v79, v133
	v_cmp_gt_f32_e32 vcc, v79, v145
	s_cbranch_vccz .LBB0_692
	v_max_f32_e32 v79, v79, v79
	v_max_f32_e32 v133, v145, v145
	v_max_f32_e32 v79, v133, v79
	v_sub_f32_e32 v133, v145, v79
	v_exp_f32_e32 v134, v133
	v_mov_b32_e32 v145, v79
	v_mul_f32_e32 v156, v156, v134
	v_pk_mul_f32 v[30:31], v[30:31], v[134:135] op_sel_hi:[1,0]
	v_pk_mul_f32 v[28:29], v[28:29], v[134:135] op_sel_hi:[1,0]
	v_pk_mul_f32 v[26:27], v[26:27], v[134:135] op_sel_hi:[1,0]
	v_pk_mul_f32 v[24:25], v[24:25], v[134:135] op_sel_hi:[1,0]
	v_pk_mul_f32 v[22:23], v[22:23], v[134:135] op_sel_hi:[1,0]
	v_pk_mul_f32 v[20:21], v[20:21], v[134:135] op_sel_hi:[1,0]
	v_pk_mul_f32 v[18:19], v[18:19], v[134:135] op_sel_hi:[1,0]
	v_pk_mul_f32 v[16:17], v[16:17], v[134:135] op_sel_hi:[1,0]
	v_pk_mul_f32 v[14:15], v[14:15], v[134:135] op_sel_hi:[1,0]
	v_pk_mul_f32 v[12:13], v[12:13], v[134:135] op_sel_hi:[1,0]
	v_pk_mul_f32 v[10:11], v[10:11], v[134:135] op_sel_hi:[1,0]
	v_pk_mul_f32 v[8:9], v[8:9], v[134:135] op_sel_hi:[1,0]
	v_pk_mul_f32 v[6:7], v[6:7], v[134:135] op_sel_hi:[1,0]
	v_pk_mul_f32 v[4:5], v[4:5], v[134:135] op_sel_hi:[1,0]
	v_pk_mul_f32 v[2:3], v[2:3], v[134:135] op_sel_hi:[1,0]
	v_pk_mul_f32 v[0:1], v[0:1], v[134:135] op_sel_hi:[1,0]

; template <class MB, int V1, class VS> __device__ __forceinline__ void la_step(LA& st, const bf16x8 (&qf)[4], Frag& f, const char* kb, const VS& vs, const TP& t, const TP& n) {
;     f32x16 s = zero16();
; #pragma unroll
;     for (int d0 = 0; d0 < 4; ++d0) s = __builtin_amdgcn_mfma_f32_32x32x16_bf16(f.k[d0], qf[d0], s, 0, 0, 0);
;     la_loadK(f, kb, n);
;     float mx = NEGBIG;
; #pragma unroll
;     for (int r = 0; r < 16; ++r) { s[r] = MB::apply(t, r, s[r]); mx = __builtin_fmaxf(mx, s[r]); }
;     { auto rr = __builtin_amdgcn_permlane32_swap(__float_as_uint(mx), __float_as_uint(mx), false, false); mx = __builtin_fmaxf(__uint_as_float(rr[0]), __uint_as_float(rr[1])); }
;     if (__any(mx > st.m)) { const float mn = __builtin_fmaxf(st.m, mx), alpha = __builtin_amdgcn_exp2f(st.m - mn); st.m = mn; st.l *= alpha; st.o0 *= alpha; st.o1 *= alpha; }
;     float rs = 0.f;
; #pragma unroll
;     for (int r = 0; r < 16; ++r) { s[r] = __builtin_amdgcn_exp2f(s[r] - st.m); rs += s[r]; }
.LBB0_696:
	v_lshlrev_b32_e32 v0, 1, v1
	v_ashrrev_i32_e32 v1, 31, v0
	v_lshl_add_u64 v[0:1], s[72:73], 0, v[0:1]
	v_add_co_u32_e32 v2, vcc, 0x100000, v0
	s_add_i32 s11, s1, s8
	s_nop 0
	v_addc_co_u32_e32 v3, vcc, 0, v1, vcc
	s_cmpk_lt_u32 s11, 0x400
	s_cselect_b64 vcc, -1, 0
	s_mov_b32 s10, s8
	s_and_b64 s[8:9], vcc, exec
	s_cselect_b32 s8, s11, s1
	global_load_dwordx4 v[64:67], v[2:3], off offset:2080
	global_load_dwordx4 v[68:71], v[2:3], off offset:2048
	global_load_dwordx4 v[72:75], v[0:1], off offset:32
	global_load_dwordx4 v[76:79], v[0:1], off
	v_lshl_add_u32 v0, s8, 6, v113
	s_add_i32 s8, s10, 32
	s_cmp_lg_u32 s10, 64
	s_cselect_b32 s9, s8, 64
	s_add_i32 s9, s9, s1
	s_cmpk_lt_u32 s9, 0x400
	v_add_u32_e32 v0, 0x4210, v0
	v_mov_b32_e32 v1, s53
	s_cselect_b32 s9, s9, s1
	v_cndmask_b32_e32 v118, v1, v0, vcc
	v_lshl_add_u32 v0, s9, 4, v112
	v_mul_lo_u32 v0, v0, s67
	v_add_lshl_u32 v114, v0, v181, 1
	s_nop 0
	s_waitcnt vmcnt(7)
	v_mfma_f32_32x32x16_bf16 v[0:15], v[60:63], v[80:83], 0
	s_waitcnt vmcnt(6)
	v_mfma_f32_32x32x16_bf16 v[0:15], v[56:59], v[88:91], v[0:15]
	s_waitcnt vmcnt(5)
	v_mfma_f32_32x32x16_bf16 v[0:15], v[52:55], v[96:99], v[0:15]
	s_waitcnt vmcnt(4)
	v_mfma_f32_32x32x16_bf16 v[0:15], v[48:51], v[104:107], v[0:15]
	global_load_dwordx4 v[60:63], v114, s[74:75]
	global_load_dwordx4 v[56:59], v114, s[74:75] offset:32
	global_load_dwordx4 v[52:55], v114, s[74:75] offset:64
	global_load_dwordx4 v[48:51], v114, s[74:75] offset:96
	ds_read2_b32 v[114:115], v118 offset1:16
	ds_read2_b32 v[116:117], v118 offset0:32 offset1:48
	s_waitcnt lgkmcnt(1)
	s_nop 4
	v_add_f32_e32 v114, v0, v114
	v_add_f32_e32 v0, v1, v115
	s_waitcnt lgkmcnt(0)
	v_add_f32_e32 v115, v2, v116
	v_add_f32_e32 v2, v3, v117
	ds_read2_b32 v[116:117], v118 offset0:64 offset1:80
	v_max3_f32 v1, v114, s2, v0
	v_max3_f32 v1, v1, v115, v2
	s_waitcnt lgkmcnt(0)
	v_add_f32_e32 v4, v4, v116
	v_add_f32_e32 v3, v5, v117
	ds_read2_b32 v[116:117], v118 offset0:96 offset1:112
	v_add_u32_e32 v118, 0x400, v118
	v_max3_f32 v1, v1, v4, v3
	s_waitcnt lgkmcnt(0)
	v_add_f32_e32 v6, v6, v116
	v_add_f32_e32 v5, v7, v117
	ds_read2_b32 v[116:117], v118 offset1:16
	v_max3_f32 v1, v1, v6, v5
	s_waitcnt lgkmcnt(0)
	v_add_f32_e32 v8, v8, v116
	v_add_f32_e32 v7, v9, v117
	ds_read2_b32 v[116:117], v118 offset0:32 offset1:48
	v_max3_f32 v1, v1, v8, v7
	s_waitcnt lgkmcnt(0)
	v_add_f32_e32 v10, v10, v116
	v_add_f32_e32 v9, v11, v117
	ds_read2_b32 v[116:117], v118 offset0:64 offset1:80
	v_max3_f32 v1, v1, v10, v9
	s_waitcnt lgkmcnt(0)
	v_add_f32_e32 v12, v12, v116
	v_add_f32_e32 v11, v13, v117
	ds_read2_b32 v[116:117], v118 offset0:96 offset1:112
	v_max3_f32 v1, v1, v12, v11
	s_waitcnt lgkmcnt(0)
	v_add_f32_e32 v14, v14, v116
	v_add_f32_e32 v13, v15, v117
	v_max3_f32 v1, v1, v14, v13
	v_mov_b32_e32 v15, v1
	s_nop 1
	v_permlane32_swap_b32_e32 v1, v15
	v_max_f32_e32 v15, v15, v15
	v_max_f32_e32 v1, v1, v1
	v_max_f32_e32 v1, v1, v15
	v_cmp_gt_f32_e32 vcc, v1, v145
	s_cbranch_vccz .LBB0_695
	v_max_f32_e32 v1, v1, v1
	v_max_f32_e32 v15, v145, v145
	v_max_f32_e32 v1, v15, v1
	v_sub_f32_e32 v15, v145, v1
	v_exp_f32_e32 v116, v15
	v_mov_b32_e32 v145, v1
	v_mul_f32_e32 v158, v158, v116
	v_pk_mul_f32 v[46:47], v[46:47], v[116:117] op_sel_hi:[1,0]
	v_pk_mul_f32 v[44:45], v[44:45], v[116:117] op_sel_hi:[1,0]
	v_pk_mul_f32 v[42:43], v[42:43], v[116:117] op_sel_hi:[1,0]
	v_pk_mul_f32 v[40:41], v[40:41], v[116:117] op_sel_hi:[1,0]
	v_pk_mul_f32 v[38:39], v[38:39], v[116:117] op_sel_hi:[1,0]
	v_pk_mul_f32 v[36:37], v[36:37], v[116:117] op_sel_hi:[1,0]
	v_pk_mul_f32 v[34:35], v[34:35], v[116:117] op_sel_hi:[1,0]
	v_pk_mul_f32 v[32:33], v[32:33], v[116:117] op_sel_hi:[1,0]
	v_pk_mul_f32 v[30:31], v[30:31], v[116:117] op_sel_hi:[1,0]
	v_pk_mul_f32 v[28:29], v[28:29], v[116:117] op_sel_hi:[1,0]
	v_pk_mul_f32 v[26:27], v[26:27], v[116:117] op_sel_hi:[1,0]
	v_pk_mul_f32 v[24:25], v[24:25], v[116:117] op_sel_hi:[1,0]
	v_pk_mul_f32 v[22:23], v[22:23], v[116:117] op_sel_hi:[1,0]
	v_pk_mul_f32 v[20:21], v[20:21], v[116:117] op_sel_hi:[1,0]
	v_pk_mul_f32 v[18:19], v[18:19], v[116:117] op_sel_hi:[1,0]
	v_pk_mul_f32 v[16:17], v[16:17], v[116:117] op_sel_hi:[1,0]
	s_branch .LBB0_695

; template <class MB, int V1, class VS> __device__ __forceinline__ void la_step(LA& st, const bf16x8 (&qf)[4], Frag& f, const char* kb, const VS& vs, const TP& t, const TP& n) {
;     f32x16 s = zero16();
; #pragma unroll
;     for (int d0 = 0; d0 < 4; ++d0) s = __builtin_amdgcn_mfma_f32_32x32x16_bf16(f.k[d0], qf[d0], s, 0, 0, 0);
;     la_loadK(f, kb, n);
;     float mx = NEGBIG;
; #pragma unroll
;     for (int r = 0; r < 16; ++r) { s[r] = MB::apply(t, r, s[r]); mx = __builtin_fmaxf(mx, s[r]); }
;     { auto rr = __builtin_amdgcn_permlane32_swap(__float_as_uint(mx), __float_as_uint(mx), false, false); mx = __builtin_fmaxf(__uint_as_float(rr[0]), __uint_as_float(rr[1])); }
;     if (__any(mx > st.m)) { const float mn = __builtin_fmaxf(st.m, mx), alpha = __builtin_amdgcn_exp2f(st.m - mn); st.m = mn; st.l *= alpha; st.o0 *= alpha; st.o1 *= alpha; }
;     float rs = 0.f;
; #pragma unroll
;     for (int r = 0; r < 16; ++r) { s[r] = __builtin_amdgcn_exp2f(s[r] - st.m); rs += s[r]; }
.LBB0_700:
	v_lshlrev_b32_e32 v64, 1, v79
	v_ashrrev_i32_e32 v65, 31, v64
	v_lshl_add_u64 v[64:65], s[72:73], 0, v[64:65]
	s_mov_b32 s8, s4
	global_load_dwordx4 v[140:143], v[64:65], off
	global_load_dwordx4 v[136:139], v[64:65], off offset:32
	v_add_co_u32_e32 v64, vcc, s80, v64
	s_add_i32 s4, s1, s4
	s_nop 0
	v_addc_co_u32_e32 v65, vcc, 0, v65, vcc
	s_cmpk_lt_u32 s4, 0x400
	s_cselect_b64 vcc, -1, 0
	s_and_b64 s[6:7], vcc, exec
	s_cselect_b32 s4, s4, s1
	global_load_dwordx4 v[132:135], v[64:65], off offset:2048
	global_load_dwordx4 v[128:131], v[64:65], off offset:2080
	v_lshl_add_u32 v64, s4, 6, v161
	s_add_i32 s4, s8, 32
	s_cmp_lg_u32 s8, 64
	s_cselect_b32 s6, s4, 64
	s_add_i32 s6, s6, s1
	s_cmpk_lt_u32 s6, 0x400
	v_add_u32_e32 v64, 0x4210, v64
	v_mov_b32_e32 v65, s53
	s_cselect_b32 s6, s6, s1
	v_cndmask_b32_e32 v166, v65, v64, vcc
	v_lshl_add_u32 v64, s6, 4, v160
	v_mul_lo_u32 v64, v64, s67
	v_add_lshl_u32 v162, v64, v181, 1
	s_nop 0
	s_waitcnt vmcnt(7)
	v_mfma_f32_32x32x16_bf16 v[64:79], v[124:127], v[84:87], 0
	s_waitcnt vmcnt(6)
	v_mfma_f32_32x32x16_bf16 v[64:79], v[120:123], v[92:95], v[64:79]
	s_waitcnt vmcnt(5)
	v_mfma_f32_32x32x16_bf16 v[64:79], v[116:119], v[100:103], v[64:79]
	s_waitcnt vmcnt(4)
	v_mfma_f32_32x32x16_bf16 v[64:79], v[112:115], v[108:111], v[64:79]
	global_load_dwordx4 v[124:127], v162, s[74:75]
	global_load_dwordx4 v[120:123], v162, s[74:75] offset:32
	global_load_dwordx4 v[116:119], v162, s[74:75] offset:64
	global_load_dwordx4 v[112:115], v162, s[74:75] offset:96
	ds_read2_b32 v[162:163], v166 offset1:16
	ds_read2_b32 v[164:165], v166 offset0:32 offset1:48
	s_waitcnt lgkmcnt(1)
	s_nop 4
	v_add_f32_e32 v162, v64, v162
	v_add_f32_e32 v64, v65, v163
	s_waitcnt lgkmcnt(0)
	v_add_f32_e32 v66, v66, v164
	v_add_f32_e32 v65, v67, v165
	ds_read2_b32 v[164:165], v166 offset0:64 offset1:80
	v_max3_f32 v163, v162, s2, v64
	v_max3_f32 v163, v163, v66, v65
	s_waitcnt lgkmcnt(0)
	v_add_f32_e32 v68, v68, v164
	v_add_f32_e32 v67, v69, v165
	ds_read2_b32 v[164:165], v166 offset0:96 offset1:112
	v_add_u32_e32 v166, 0x400, v166
	v_max3_f32 v163, v163, v68, v67
	s_waitcnt lgkmcnt(0)
	v_add_f32_e32 v70, v70, v164
	v_add_f32_e32 v69, v71, v165
	ds_read2_b32 v[164:165], v166 offset1:16
	v_max3_f32 v163, v163, v70, v69
	s_waitcnt lgkmcnt(0)
	v_add_f32_e32 v72, v72, v164
	v_add_f32_e32 v71, v73, v165
	ds_read2_b32 v[164:165], v166 offset0:32 offset1:48
	v_max3_f32 v163, v163, v72, v71
	s_waitcnt lgkmcnt(0)
	v_add_f32_e32 v74, v74, v164
	v_add_f32_e32 v73, v75, v165
	ds_read2_b32 v[164:165], v166 offset0:64 offset1:80
	v_max3_f32 v163, v163, v74, v73
	s_waitcnt lgkmcnt(0)
	v_add_f32_e32 v76, v76, v164
	v_add_f32_e32 v75, v77, v165
	ds_read2_b32 v[164:165], v166 offset0:96 offset1:112
	v_max3_f32 v163, v163, v76, v75
	s_waitcnt lgkmcnt(0)
	v_add_f32_e32 v78, v78, v164
	v_add_f32_e32 v77, v79, v165
	v_max3_f32 v79, v163, v78, v77
	v_mov_b32_e32 v163, v79
	s_nop 1
	v_permlane32_swap_b32_e32 v79, v163
	v_max_f32_e32 v163, v163, v163
	v_max_f32_e32 v79, v79, v79
	v_max_f32_e32 v79, v79, v163
	v_cmp_gt_f32_e32 vcc, v79, v149
	s_cbranch_vccz .LBB0_699
	v_max_f32_e32 v79, v79, v79
	v_max_f32_e32 v163, v149, v149
	v_max_f32_e32 v79, v163, v79
	v_sub_f32_e32 v149, v149, v79
	v_exp_f32_e32 v164, v149
	v_mov_b32_e32 v149, v79
	v_mul_f32_e32 v156, v156, v164
	v_pk_mul_f32 v[62:63], v[62:63], v[164:165] op_sel_hi:[1,0]
	v_pk_mul_f32 v[60:61], v[60:61], v[164:165] op_sel_hi:[1,0]
	v_pk_mul_f32 v[58:59], v[58:59], v[164:165] op_sel_hi:[1,0]
	v_pk_mul_f32 v[56:57], v[56:57], v[164:165] op_sel_hi:[1,0]
	v_pk_mul_f32 v[54:55], v[54:55], v[164:165] op_sel_hi:[1,0]
	v_pk_mul_f32 v[52:53], v[52:53], v[164:165] op_sel_hi:[1,0]
	v_pk_mul_f32 v[50:51], v[50:51], v[164:165] op_sel_hi:[1,0]
	v_pk_mul_f32 v[48:49], v[48:49], v[164:165] op_sel_hi:[1,0]
	v_pk_mul_f32 v[14:15], v[14:15], v[164:165] op_sel_hi:[1,0]
	v_pk_mul_f32 v[12:13], v[12:13], v[164:165] op_sel_hi:[1,0]
	v_pk_mul_f32 v[10:11], v[10:11], v[164:165] op_sel_hi:[1,0]
	v_pk_mul_f32 v[8:9], v[8:9], v[164:165] op_sel_hi:[1,0]
	v_pk_mul_f32 v[6:7], v[6:7], v[164:165] op_sel_hi:[1,0]
	v_pk_mul_f32 v[4:5], v[4:5], v[164:165] op_sel_hi:[1,0]
	v_pk_mul_f32 v[2:3], v[2:3], v[164:165] op_sel_hi:[1,0]
	v_pk_mul_f32 v[0:1], v[0:1], v[164:165] op_sel_hi:[1,0]
	s_branch .LBB0_699

; __device__ __forceinline__ unsigned xb_lane() { unsigned l = __builtin_amdgcn_mbcnt_hi(~0u, __builtin_amdgcn_mbcnt_lo(~0u, 0u)); asm volatile("" : "+v"(l)); return l; }
; __device__ __forceinline__ void xcd_barrier(const XcdBarrier& b) {
;     asm volatile("s_waitcnt vmcnt(0)" ::: "memory");
;     __syncthreads();
;     if (b.lead != 0u && xb_lane() == 0u) {
;         unsigned* bar = b.bar;
;         __builtin_amdgcn_s_waitcnt(0);
;         unsigned nloc = b.st[0], nx = b.st[1];
;         if (nloc == 0u) { xcd_barrier_complete(bar, b.x, nloc, nx); b.st[0] = nloc; b.st[1] = nx; }
.LBB0_709:
	s_add_i32 s0, s36, 4
	s_cmp_lt_i32 s0, s51
	s_cselect_b64 s[4:5], -1, 0
	s_and_b64 s[6:7], s[46:47], s[4:5]
	s_andn2_b64 vcc, exec, s[6:7]
	s_cbranch_vccnz .LBB0_796
	v_readlane_b32 s8, v255, 3
	v_readlane_b32 s9, v255, 4
	s_mov_b64 s[6:7], -1
	s_and_b64 vcc, exec, s[8:9]
	s_cbranch_vccz .LBB0_783
	v_readfirstlane_b32 s6, v251
	v_readlane_b32 s1, v255, 2
	s_waitcnt vmcnt(0)
	s_cmp_eq_u32 s6, 0
	s_waitcnt vmcnt(0)
	s_barrier
	s_cbranch_scc1 .LBB0_782
	v_mov_b32_e32 v0, v252
	s_nop 0
	v_cmp_eq_u32_e32 vcc, 0, v0
	s_and_saveexec_b64 s[6:7], vcc
	s_cbranch_execz .LBB0_781
	v_readlane_b32 s8, v255, 26
	s_waitcnt vmcnt(0) expcnt(0) lgkmcnt(0)
	s_nop 0
	v_mov_b32_e32 v0, s8
	ds_read_b32 v2, v0
	v_readlane_b32 s8, v255, 27
	s_waitcnt lgkmcnt(0)
	v_cmp_ne_u32_e32 vcc, 0, v2
	v_mov_b32_e32 v0, s8
	ds_read_b32 v0, v0
	s_cbranch_vccnz .LBB0_745
	v_readlane_b32 s10, v255, 0
	v_readlane_b32 s11, v255, 1
	s_load_dwordx2 s[8:9], s[10:11], 0x4
	s_mov_b32 s15, 1
	s_waitcnt lgkmcnt(0)
	s_mul_i32 s14, s8, s3
	s_mul_i32 s14, s14, s9
	s_branch .LBB0_716
	s_nop 0
	s_nop 0
	s_nop 0
	s_nop 0
	s_nop 0
	s_nop 0
	s_nop 0
	s_nop 0
	s_nop 0
	s_nop 0
	s_nop 0
	s_nop 0
	s_nop 0
	s_nop 0
	s_nop 0
